# P5: the two wave halves no longer align their epilogues (leading half keeps its extra barrier for the last unit only, trailing half's re-offset barrier removed)
# speedup vs baseline: 1.0008x; 1.0008x over previous
.Lpeel_exit_p5:
	s_and_b64 vcc, exec, s[14:15]
	s_cbranch_vccz .LBB0_771
	s_and_b64 vcc, exec, s[6:7]
	s_cbranch_vccnz .LBB0_771
	s_barrier

.Lht_epi_done:
	s_andn2_b64 vcc, exec, s[6:7]
	s_mov_b64 s[6:7], -1
	s_cbranch_vccnz .LBB0_764
	s_andn2_b64 vcc, exec, s[10:11]
	s_cbranch_vccnz .LBB0_763
	s_branch .LBB0_763
